# K-loop: leading half takes each counted vmcnt wait at the end of its MFMA segment (one segment more cover for its LDS-DMA loads); trailing half unchanged
# baseline (speedup 1.0000x reference)
.LBB0_332:
	s_add_u32 s42, s42, 0x80
	s_addc_u32 s43, s43, 0
	s_add_u32 s48, s78, 0x100
	s_addc_u32 s49, s79, 0
	s_mov_b32 s50, 0
	v_readlane_b32 s52, v233, 50
	v_readlane_b32 s53, v233, 51
	s_and_b64 vcc, exec, s[52:53]
	v_readlane_b32 s51, v232, 60
	s_cmp_eq_u32 s51, 0
	s_cbranch_scc0 .Lk_peel
	v_mov_b32_e32 v0, 0
	v_mov_b32_e32 v1, v0
	v_mov_b32_e32 v2, v0
	v_mov_b32_e32 v3, v0
	v_mov_b32_e32 v4, v0
	v_mov_b32_e32 v5, v0
	v_mov_b32_e32 v6, v0
	v_mov_b32_e32 v7, v0
	v_mov_b32_e32 v16, v0
	v_mov_b32_e32 v17, v0
	v_mov_b32_e32 v18, v0
	v_mov_b32_e32 v19, v0
	v_mov_b32_e32 v20, v0
	v_mov_b32_e32 v21, v0
	v_mov_b32_e32 v22, v0
	v_mov_b32_e32 v23, v0
	v_mov_b32_e32 v32, v0
	v_mov_b32_e32 v33, v0
	v_mov_b32_e32 v34, v0
	v_mov_b32_e32 v35, v0
	v_mov_b32_e32 v36, v0
	v_mov_b32_e32 v37, v0
	v_mov_b32_e32 v38, v0
	v_mov_b32_e32 v39, v0
	v_mov_b32_e32 v48, v0
	v_mov_b32_e32 v49, v0
	v_mov_b32_e32 v50, v0
	v_mov_b32_e32 v51, v0
	v_mov_b32_e32 v52, v0
	v_mov_b32_e32 v53, v0
	v_mov_b32_e32 v54, v0
	v_mov_b32_e32 v55, v0
	v_mov_b32_e32 v8, v0
	v_mov_b32_e32 v9, v0
	v_mov_b32_e32 v10, v0
	v_mov_b32_e32 v11, v0
	v_mov_b32_e32 v12, v0
	v_mov_b32_e32 v13, v0
	v_mov_b32_e32 v14, v0
	v_mov_b32_e32 v15, v0
	v_mov_b32_e32 v24, v0
	v_mov_b32_e32 v25, v0
	v_mov_b32_e32 v26, v0
	v_mov_b32_e32 v27, v0
	v_mov_b32_e32 v28, v0
	v_mov_b32_e32 v29, v0
	v_mov_b32_e32 v30, v0
	v_mov_b32_e32 v31, v0
	v_mov_b32_e32 v40, v0
	v_mov_b32_e32 v41, v0
	v_mov_b32_e32 v42, v0
	v_mov_b32_e32 v43, v0
	v_mov_b32_e32 v44, v0
	v_mov_b32_e32 v45, v0
	v_mov_b32_e32 v46, v0
	v_mov_b32_e32 v47, v0
	v_mov_b32_e32 v56, v0
	v_mov_b32_e32 v57, v0
	v_mov_b32_e32 v58, v0
	v_mov_b32_e32 v59, v0
	v_mov_b32_e32 v60, v0
	v_mov_b32_e32 v61, v0
	v_mov_b32_e32 v62, v0
	v_mov_b32_e32 v63, v0
	v_mov_b32_e32 v64, v0
	v_mov_b32_e32 v65, v0
	v_mov_b32_e32 v66, v0
	v_mov_b32_e32 v67, v0
	v_mov_b32_e32 v68, v0
	v_mov_b32_e32 v69, v0
	v_mov_b32_e32 v70, v0
	v_mov_b32_e32 v71, v0
	v_mov_b32_e32 v80, v0
	v_mov_b32_e32 v81, v0
	v_mov_b32_e32 v82, v0
	v_mov_b32_e32 v83, v0
	v_mov_b32_e32 v84, v0
	v_mov_b32_e32 v85, v0
	v_mov_b32_e32 v86, v0
	v_mov_b32_e32 v87, v0
	v_mov_b32_e32 v98, v0
	v_mov_b32_e32 v99, v0
	v_mov_b32_e32 v100, v0
	v_mov_b32_e32 v101, v0
	v_mov_b32_e32 v102, v0
	v_mov_b32_e32 v103, v0
	v_mov_b32_e32 v104, v0
	v_mov_b32_e32 v105, v0
	v_mov_b32_e32 v114, v0
	v_mov_b32_e32 v115, v0
	v_mov_b32_e32 v116, v0
	v_mov_b32_e32 v117, v0
	v_mov_b32_e32 v118, v0
	v_mov_b32_e32 v119, v0
	v_mov_b32_e32 v120, v0
	v_mov_b32_e32 v121, v0
	v_mov_b32_e32 v72, v0
	v_mov_b32_e32 v73, v0
	v_mov_b32_e32 v74, v0
	v_mov_b32_e32 v75, v0
	v_mov_b32_e32 v76, v0
	v_mov_b32_e32 v77, v0
	v_mov_b32_e32 v78, v0
	v_mov_b32_e32 v79, v0
	v_mov_b32_e32 v88, v0
	v_mov_b32_e32 v89, v0
	v_mov_b32_e32 v90, v0
	v_mov_b32_e32 v91, v0
	v_mov_b32_e32 v92, v0
	v_mov_b32_e32 v93, v0
	v_mov_b32_e32 v94, v0
	v_mov_b32_e32 v95, v0
	v_mov_b32_e32 v106, v0
	v_mov_b32_e32 v107, v0
	v_mov_b32_e32 v108, v0
	v_mov_b32_e32 v109, v0
	v_mov_b32_e32 v110, v0
	v_mov_b32_e32 v111, v0
	v_mov_b32_e32 v112, v0
	v_mov_b32_e32 v113, v0
	v_mov_b32_e32 v122, v0
	v_mov_b32_e32 v123, v0
	v_mov_b32_e32 v124, v0
	v_mov_b32_e32 v125, v0
	v_mov_b32_e32 v126, v0
	v_mov_b32_e32 v127, v0
	v_mov_b32_e32 v128, v0
	v_mov_b32_e32 v129, v0
.LBB0_333:
	s_add_i32 s51, s50, 2
	s_add_u32 s52, s42, 0x80
	s_addc_u32 s53, s43, 0
	s_add_i32 s54, 0, 0x10000
	s_cmp_eq_u32 s87, s50
	s_cselect_b32 s79, s1, s53
	s_cselect_b32 s78, s0, s52
	v_add_u32_e32 v144, s54, v147
	s_cselect_b32 s53, s75, s49
	s_cselect_b32 s52, s74, s48
	s_add_i32 s50, 0, 0x14000
	s_waitcnt lgkmcnt(0)
	ds_read_b128 v[140:143], v144
	ds_read_b128 v[162:165], v144 offset:1024
	ds_read_b128 v[166:169], v144 offset:2048
	ds_read_b128 v[170:173], v144 offset:3072
	v_add_u32_e32 v144, s50, v147
	ds_read_b128 v[174:177], v144
	ds_read_b128 v[178:181], v144 offset:1024
	ds_read_b128 v[182:185], v144 offset:2048
	ds_read_b128 v[186:189], v144 offset:3072
	v_lshl_add_u64 v[144:145], s[42:43], 0, v[136:137]
	s_add_i32 m0, s9, 0xc000
	ds_read_b128 v[190:193], v149
	ds_read_b128 v[194:197], v149 offset:1024
	ds_read_b128 v[198:201], v149 offset:2048
	ds_read_b128 v[202:205], v149 offset:3072
	ds_read_b128 v[206:209], v149 offset:4096
	ds_read_b128 v[210:213], v149 offset:5120
	ds_read_b128 v[214:217], v149 offset:6144
	ds_read_b128 v[218:221], v149 offset:7168
	global_load_lds_dwordx4 v[144:145], off
	v_lshl_add_u64 v[144:145], s[42:43], 0, v[138:139]
	s_add_i32 m0, s9, 0xe000
	s_nop 0
	global_load_lds_dwordx4 v[144:145], off
	s_cbranch_vccnz .Llw_m0_a
	s_waitcnt vmcnt(8)
.Llw_m0_a:
	s_waitcnt lgkmcnt(0)
	s_barrier
	s_setprio 1
	s_waitcnt lgkmcnt(0)
	v_mfma_f32_16x16x32_bf16 v[126:129], v[140:143], v[190:193], v[126:129]
	v_mfma_f32_16x16x32_bf16 v[122:125], v[166:169], v[190:193], v[122:125]
	v_mfma_f32_16x16x32_bf16 v[110:113], v[140:143], v[198:201], v[110:113]
	v_mfma_f32_16x16x32_bf16 v[106:109], v[166:169], v[198:201], v[106:109]
	v_mfma_f32_16x16x32_bf16 v[92:95], v[140:143], v[206:209], v[92:95]
	v_mfma_f32_16x16x32_bf16 v[88:91], v[166:169], v[206:209], v[88:91]
	v_mfma_f32_16x16x32_bf16 v[76:79], v[140:143], v[214:217], v[76:79]
	v_mfma_f32_16x16x32_bf16 v[72:75], v[166:169], v[214:217], v[72:75]
	v_mfma_f32_16x16x32_bf16 v[126:129], v[162:165], v[194:197], v[126:129]
	v_mfma_f32_16x16x32_bf16 v[122:125], v[170:173], v[194:197], v[122:125]
	v_mfma_f32_16x16x32_bf16 v[110:113], v[162:165], v[202:205], v[110:113]
	v_mfma_f32_16x16x32_bf16 v[106:109], v[170:173], v[202:205], v[106:109]
	v_mfma_f32_16x16x32_bf16 v[92:95], v[162:165], v[210:213], v[92:95]
	v_mfma_f32_16x16x32_bf16 v[88:91], v[170:173], v[210:213], v[88:91]
	v_mfma_f32_16x16x32_bf16 v[76:79], v[162:165], v[218:221], v[76:79]
	v_mfma_f32_16x16x32_bf16 v[72:75], v[170:173], v[218:221], v[72:75]
	s_setprio 0
	s_setprio 1
	v_mfma_f32_16x16x32_bf16 v[118:121], v[174:177], v[190:193], v[118:121]
	v_mfma_f32_16x16x32_bf16 v[114:117], v[182:185], v[190:193], v[114:117]
	v_mfma_f32_16x16x32_bf16 v[102:105], v[174:177], v[198:201], v[102:105]
	v_mfma_f32_16x16x32_bf16 v[98:101], v[182:185], v[198:201], v[98:101]
	v_mfma_f32_16x16x32_bf16 v[84:87], v[174:177], v[206:209], v[84:87]
	v_mfma_f32_16x16x32_bf16 v[80:83], v[182:185], v[206:209], v[80:83]
	v_mfma_f32_16x16x32_bf16 v[68:71], v[174:177], v[214:217], v[68:71]
	v_mfma_f32_16x16x32_bf16 v[64:67], v[182:185], v[214:217], v[64:67]
	v_mfma_f32_16x16x32_bf16 v[118:121], v[178:181], v[194:197], v[118:121]
	v_mfma_f32_16x16x32_bf16 v[114:117], v[186:189], v[194:197], v[114:117]
	v_mfma_f32_16x16x32_bf16 v[102:105], v[178:181], v[202:205], v[102:105]
	v_mfma_f32_16x16x32_bf16 v[98:101], v[186:189], v[202:205], v[98:101]
	v_mfma_f32_16x16x32_bf16 v[84:87], v[178:181], v[210:213], v[84:87]
	v_mfma_f32_16x16x32_bf16 v[80:83], v[186:189], v[210:213], v[80:83]
	v_mfma_f32_16x16x32_bf16 v[68:71], v[178:181], v[218:221], v[68:71]
	v_mfma_f32_16x16x32_bf16 v[64:67], v[186:189], v[218:221], v[64:67]
	s_setprio 0
	s_cbranch_vccz .Llw_m0_b
	s_waitcnt vmcnt(8)
.Llw_m0_b:
	s_barrier
	s_add_i32 s54, s54, s8
	v_lshl_add_u64 v[144:145], s[52:53], 0, v[96:97]
	s_mov_b32 m0, s54
	ds_read_b128 v[190:193], v149 offset:16384
	ds_read_b128 v[194:197], v149 offset:17408
	ds_read_b128 v[198:201], v149 offset:18432
	ds_read_b128 v[202:205], v149 offset:19456
	ds_read_b128 v[206:209], v149 offset:20480
	ds_read_b128 v[210:213], v149 offset:21504
	ds_read_b128 v[214:217], v149 offset:22528
	ds_read_b128 v[218:221], v149 offset:23552
	global_load_lds_dwordx4 v[144:145], off
	s_add_i32 m0, s54, 0x2000
	v_lshl_add_u64 v[150:151], s[52:53], 0, v[134:135]
	s_add_u32 s52, s52, s34
	s_addc_u32 s53, s53, s35
	s_add_i32 s50, s50, s8
	global_load_lds_dwordx4 v[150:151], off
	v_lshl_add_u64 v[222:223], s[52:53], 0, v[96:97]
	s_mov_b32 m0, s50
	v_lshl_add_u64 v[224:225], s[52:53], 0, v[134:135]
	global_load_lds_dwordx4 v[222:223], off
	s_add_i32 m0, s50, 0x2000
	v_lshl_add_u64 v[226:227], s[78:79], 0, v[130:131]
	global_load_lds_dwordx4 v[224:225], off
	s_mov_b32 m0, s9
	v_lshl_add_u64 v[228:229], s[78:79], 0, v[132:133]
	global_load_lds_dwordx4 v[226:227], off
	s_mov_b32 m0, s98
	s_nop 0
	global_load_lds_dwordx4 v[228:229], off
	s_cbranch_vccnz .Llw_m1_a
	s_waitcnt vmcnt(8)
.Llw_m1_a:
	s_waitcnt lgkmcnt(0)
	s_barrier
	s_setprio 1
	s_waitcnt lgkmcnt(0)
	v_mfma_f32_16x16x32_bf16 v[60:63], v[140:143], v[190:193], v[60:63]
	v_mfma_f32_16x16x32_bf16 v[56:59], v[166:169], v[190:193], v[56:59]
	v_mfma_f32_16x16x32_bf16 v[44:47], v[140:143], v[198:201], v[44:47]
	v_mfma_f32_16x16x32_bf16 v[40:43], v[166:169], v[198:201], v[40:43]
	v_mfma_f32_16x16x32_bf16 v[28:31], v[140:143], v[206:209], v[28:31]
	v_mfma_f32_16x16x32_bf16 v[24:27], v[166:169], v[206:209], v[24:27]
	v_mfma_f32_16x16x32_bf16 v[12:15], v[140:143], v[214:217], v[12:15]
	v_mfma_f32_16x16x32_bf16 v[8:11], v[166:169], v[214:217], v[8:11]
	v_mfma_f32_16x16x32_bf16 v[60:63], v[162:165], v[194:197], v[60:63]
	v_mfma_f32_16x16x32_bf16 v[56:59], v[170:173], v[194:197], v[56:59]
	v_mfma_f32_16x16x32_bf16 v[44:47], v[162:165], v[202:205], v[44:47]
	v_mfma_f32_16x16x32_bf16 v[40:43], v[170:173], v[202:205], v[40:43]
	v_mfma_f32_16x16x32_bf16 v[28:31], v[162:165], v[210:213], v[28:31]
	v_mfma_f32_16x16x32_bf16 v[24:27], v[170:173], v[210:213], v[24:27]
	v_mfma_f32_16x16x32_bf16 v[12:15], v[162:165], v[218:221], v[12:15]
	v_mfma_f32_16x16x32_bf16 v[8:11], v[170:173], v[218:221], v[8:11]
	s_setprio 0
	s_setprio 1
	v_mfma_f32_16x16x32_bf16 v[52:55], v[174:177], v[190:193], v[52:55]
	v_mfma_f32_16x16x32_bf16 v[48:51], v[182:185], v[190:193], v[48:51]
	v_mfma_f32_16x16x32_bf16 v[36:39], v[174:177], v[198:201], v[36:39]
	v_mfma_f32_16x16x32_bf16 v[32:35], v[182:185], v[198:201], v[32:35]
	v_mfma_f32_16x16x32_bf16 v[20:23], v[174:177], v[206:209], v[20:23]
	v_mfma_f32_16x16x32_bf16 v[16:19], v[182:185], v[206:209], v[16:19]
	v_mfma_f32_16x16x32_bf16 v[4:7], v[174:177], v[214:217], v[4:7]
	v_mfma_f32_16x16x32_bf16 v[0:3], v[182:185], v[214:217], v[0:3]
	v_mfma_f32_16x16x32_bf16 v[52:55], v[178:181], v[194:197], v[52:55]
	v_mfma_f32_16x16x32_bf16 v[48:51], v[186:189], v[194:197], v[48:51]
	v_mfma_f32_16x16x32_bf16 v[36:39], v[178:181], v[202:205], v[36:39]
	v_mfma_f32_16x16x32_bf16 v[32:35], v[186:189], v[202:205], v[32:35]
	v_mfma_f32_16x16x32_bf16 v[20:23], v[178:181], v[210:213], v[20:23]
	v_mfma_f32_16x16x32_bf16 v[16:19], v[186:189], v[210:213], v[16:19]
	v_mfma_f32_16x16x32_bf16 v[4:7], v[178:181], v[218:221], v[4:7]
	v_mfma_f32_16x16x32_bf16 v[0:3], v[186:189], v[218:221], v[0:3]
	s_setprio 0
	s_cbranch_vccz .Llw_m1_b
	s_waitcnt vmcnt(8)
.Llw_m1_b:
	s_barrier
	s_add_i32 s50, 0, 0x18000
	v_add_u32_e32 v161, s50, v147
	s_add_i32 s54, 0, 0x1c000
	ds_read_b128 v[140:143], v161
	ds_read_b128 v[162:165], v161 offset:1024
	ds_read_b128 v[166:169], v161 offset:2048
	ds_read_b128 v[170:173], v161 offset:3072
	v_add_u32_e32 v161, s54, v147
	ds_read_b128 v[174:177], v161
	ds_read_b128 v[178:181], v161 offset:1024
	ds_read_b128 v[182:185], v161 offset:2048
	ds_read_b128 v[186:189], v161 offset:3072
	s_add_u32 s52, s78, s34
	s_addc_u32 s53, s79, s35
	s_mov_b32 m0, s99
	v_lshl_add_u64 v[230:231], s[52:53], 0, v[130:131]
	ds_read_b128 v[190:193], v149 offset:32768
	ds_read_b128 v[194:197], v149 offset:33792
	ds_read_b128 v[198:201], v149 offset:34816
	ds_read_b128 v[202:205], v149 offset:35840
	ds_read_b128 v[206:209], v149 offset:36864
	ds_read_b128 v[210:213], v149 offset:37888
	ds_read_b128 v[214:217], v149 offset:38912
	ds_read_b128 v[218:221], v149 offset:39936
	global_load_lds_dwordx4 v[230:231], off
	v_lshl_add_u64 v[230:231], s[52:53], 0, v[132:133]
	s_mov_b32 m0, s76
	s_nop 0
	global_load_lds_dwordx4 v[230:231], off
	s_cbranch_vccnz .Llw_m2_a
	s_waitcnt vmcnt(8)

.Llw_m2_b:
	s_barrier
	s_add_i32 s50, s50, s8
	v_lshl_add_u64 v[144:145], v[144:145], 0, s[12:13]
	s_mov_b32 m0, s50
	ds_read_b128 v[190:193], v149 offset:49152
	ds_read_b128 v[194:197], v149 offset:50176
	ds_read_b128 v[198:201], v149 offset:51200
	ds_read_b128 v[202:205], v149 offset:52224
	ds_read_b128 v[206:209], v149 offset:53248
	ds_read_b128 v[210:213], v149 offset:54272
	ds_read_b128 v[214:217], v149 offset:55296
	ds_read_b128 v[218:221], v149 offset:56320
	global_load_lds_dwordx4 v[144:145], off
	v_lshl_add_u64 v[144:145], v[150:151], 0, s[12:13]
	s_add_i32 m0, s50, 0x2000
	s_add_i32 s50, s54, s8
	global_load_lds_dwordx4 v[144:145], off
	v_lshl_add_u64 v[144:145], v[222:223], 0, s[12:13]
	s_mov_b32 m0, s50
	s_nop 0
	global_load_lds_dwordx4 v[144:145], off
	v_lshl_add_u64 v[144:145], v[224:225], 0, s[12:13]
	s_add_i32 m0, s50, 0x2000
	s_nop 0
	global_load_lds_dwordx4 v[144:145], off
	v_lshl_add_u64 v[144:145], v[226:227], 0, s[12:13]
	s_mov_b32 m0, s77
	s_nop 0
	global_load_lds_dwordx4 v[144:145], off
	v_lshl_add_u64 v[144:145], v[228:229], 0, s[12:13]
	s_mov_b32 m0, s86
	s_nop 0
	global_load_lds_dwordx4 v[144:145], off
	s_cbranch_vccnz .Llw_m3_a
	s_waitcnt vmcnt(8)

.Llw_m3_b:
	s_barrier
	s_add_u32 s42, s42, 0x100
	s_addc_u32 s43, s43, 0
	s_add_u32 s48, s48, 0x100
	s_addc_u32 s49, s49, 0
	s_cmp_ge_u32 s51, s64
	s_mov_b32 s50, s51
	s_cbranch_scc0 .LBB0_333

.Lk_peel:
	s_add_i32 s51, s50, 2
	s_add_u32 s52, s42, 0x80
	s_addc_u32 s53, s43, 0
	s_add_i32 s54, 0, 0x10000
	s_cmp_eq_u32 s87, s50
	s_cselect_b32 s79, s1, s53
	s_cselect_b32 s78, s0, s52
	v_add_u32_e32 v144, s54, v147
	s_cselect_b32 s53, s75, s49
	s_cselect_b32 s52, s74, s48
	s_add_i32 s50, 0, 0x14000
	s_waitcnt lgkmcnt(0)
	ds_read_b128 v[140:143], v144
	ds_read_b128 v[162:165], v144 offset:1024
	ds_read_b128 v[166:169], v144 offset:2048
	ds_read_b128 v[170:173], v144 offset:3072
	v_add_u32_e32 v144, s50, v147
	ds_read_b128 v[174:177], v144
	ds_read_b128 v[178:181], v144 offset:1024
	ds_read_b128 v[182:185], v144 offset:2048
	ds_read_b128 v[186:189], v144 offset:3072
	ds_read_b128 v[190:193], v149
	ds_read_b128 v[194:197], v149 offset:1024
	ds_read_b128 v[198:201], v149 offset:2048
	ds_read_b128 v[202:205], v149 offset:3072
	ds_read_b128 v[206:209], v149 offset:4096
	ds_read_b128 v[210:213], v149 offset:5120
	ds_read_b128 v[214:217], v149 offset:6144
	ds_read_b128 v[218:221], v149 offset:7168
	s_cbranch_vccnz .Llw_p0_a
	s_waitcnt vmcnt(16)
.Llw_p0_a:
	s_waitcnt lgkmcnt(0)
	s_barrier
	s_setprio 1
	s_waitcnt lgkmcnt(0)
	v_mfma_f32_16x16x32_bf16 v[126:129], v[140:143], v[190:193], 0
	v_mfma_f32_16x16x32_bf16 v[122:125], v[166:169], v[190:193], 0
	v_mfma_f32_16x16x32_bf16 v[110:113], v[140:143], v[198:201], 0
	v_mfma_f32_16x16x32_bf16 v[106:109], v[166:169], v[198:201], 0
	v_mfma_f32_16x16x32_bf16 v[92:95], v[140:143], v[206:209], 0
	v_mfma_f32_16x16x32_bf16 v[88:91], v[166:169], v[206:209], 0
	v_mfma_f32_16x16x32_bf16 v[76:79], v[140:143], v[214:217], 0
	v_mfma_f32_16x16x32_bf16 v[72:75], v[166:169], v[214:217], 0
	v_mfma_f32_16x16x32_bf16 v[126:129], v[162:165], v[194:197], v[126:129]
	v_mfma_f32_16x16x32_bf16 v[122:125], v[170:173], v[194:197], v[122:125]
	v_mfma_f32_16x16x32_bf16 v[110:113], v[162:165], v[202:205], v[110:113]
	v_mfma_f32_16x16x32_bf16 v[106:109], v[170:173], v[202:205], v[106:109]
	v_mfma_f32_16x16x32_bf16 v[92:95], v[162:165], v[210:213], v[92:95]
	v_mfma_f32_16x16x32_bf16 v[88:91], v[170:173], v[210:213], v[88:91]
	v_mfma_f32_16x16x32_bf16 v[76:79], v[162:165], v[218:221], v[76:79]
	v_mfma_f32_16x16x32_bf16 v[72:75], v[170:173], v[218:221], v[72:75]
	s_setprio 0
	s_setprio 1
	v_mfma_f32_16x16x32_bf16 v[118:121], v[174:177], v[190:193], 0
	v_mfma_f32_16x16x32_bf16 v[114:117], v[182:185], v[190:193], 0
	v_mfma_f32_16x16x32_bf16 v[102:105], v[174:177], v[198:201], 0
	v_mfma_f32_16x16x32_bf16 v[98:101], v[182:185], v[198:201], 0
	v_mfma_f32_16x16x32_bf16 v[84:87], v[174:177], v[206:209], 0
	v_mfma_f32_16x16x32_bf16 v[80:83], v[182:185], v[206:209], 0
	v_mfma_f32_16x16x32_bf16 v[68:71], v[174:177], v[214:217], 0
	v_mfma_f32_16x16x32_bf16 v[64:67], v[182:185], v[214:217], 0
	v_mfma_f32_16x16x32_bf16 v[118:121], v[178:181], v[194:197], v[118:121]
	v_mfma_f32_16x16x32_bf16 v[114:117], v[186:189], v[194:197], v[114:117]
	v_mfma_f32_16x16x32_bf16 v[102:105], v[178:181], v[202:205], v[102:105]
	v_mfma_f32_16x16x32_bf16 v[98:101], v[186:189], v[202:205], v[98:101]
	v_mfma_f32_16x16x32_bf16 v[84:87], v[178:181], v[210:213], v[84:87]
	v_mfma_f32_16x16x32_bf16 v[80:83], v[186:189], v[210:213], v[80:83]
	v_mfma_f32_16x16x32_bf16 v[68:71], v[178:181], v[218:221], v[68:71]
	v_mfma_f32_16x16x32_bf16 v[64:67], v[186:189], v[218:221], v[64:67]
	s_setprio 0
	s_cbranch_vccz .Llw_p0_b
	s_waitcnt vmcnt(16)
.Llw_p0_b:
	s_barrier
	s_add_i32 s54, s54, s8
	v_lshl_add_u64 v[144:145], s[52:53], 0, v[96:97]
	s_mov_b32 m0, s54
	ds_read_b128 v[190:193], v149 offset:16384
	ds_read_b128 v[194:197], v149 offset:17408
	ds_read_b128 v[198:201], v149 offset:18432
	ds_read_b128 v[202:205], v149 offset:19456
	ds_read_b128 v[206:209], v149 offset:20480
	ds_read_b128 v[210:213], v149 offset:21504
	ds_read_b128 v[214:217], v149 offset:22528
	ds_read_b128 v[218:221], v149 offset:23552
	global_load_lds_dwordx4 v[144:145], off
	s_add_i32 m0, s54, 0x2000
	v_lshl_add_u64 v[150:151], s[52:53], 0, v[134:135]
	s_add_u32 s52, s52, s34
	s_addc_u32 s53, s53, s35
	s_add_i32 s50, s50, s8
	global_load_lds_dwordx4 v[150:151], off
	v_lshl_add_u64 v[222:223], s[52:53], 0, v[96:97]
	s_mov_b32 m0, s50
	v_lshl_add_u64 v[224:225], s[52:53], 0, v[134:135]
	global_load_lds_dwordx4 v[222:223], off
	s_add_i32 m0, s50, 0x2000
	v_lshl_add_u64 v[226:227], s[78:79], 0, v[130:131]
	global_load_lds_dwordx4 v[224:225], off
	s_mov_b32 m0, s9
	v_lshl_add_u64 v[228:229], s[78:79], 0, v[132:133]
	global_load_lds_dwordx4 v[226:227], off
	s_mov_b32 m0, s98
	s_nop 0
	global_load_lds_dwordx4 v[228:229], off
	s_cbranch_vccnz .Llw_p1_a
	s_waitcnt vmcnt(16)
.Llw_p1_a:
	s_waitcnt lgkmcnt(0)
	s_barrier
	s_setprio 1
	s_waitcnt lgkmcnt(0)
	v_mfma_f32_16x16x32_bf16 v[60:63], v[140:143], v[190:193], 0
	v_mfma_f32_16x16x32_bf16 v[56:59], v[166:169], v[190:193], 0
	v_mfma_f32_16x16x32_bf16 v[44:47], v[140:143], v[198:201], 0
	v_mfma_f32_16x16x32_bf16 v[40:43], v[166:169], v[198:201], 0
	v_mfma_f32_16x16x32_bf16 v[28:31], v[140:143], v[206:209], 0
	v_mfma_f32_16x16x32_bf16 v[24:27], v[166:169], v[206:209], 0
	v_mfma_f32_16x16x32_bf16 v[12:15], v[140:143], v[214:217], 0
	v_mfma_f32_16x16x32_bf16 v[8:11], v[166:169], v[214:217], 0
	v_mfma_f32_16x16x32_bf16 v[60:63], v[162:165], v[194:197], v[60:63]
	v_mfma_f32_16x16x32_bf16 v[56:59], v[170:173], v[194:197], v[56:59]
	v_mfma_f32_16x16x32_bf16 v[44:47], v[162:165], v[202:205], v[44:47]
	v_mfma_f32_16x16x32_bf16 v[40:43], v[170:173], v[202:205], v[40:43]
	v_mfma_f32_16x16x32_bf16 v[28:31], v[162:165], v[210:213], v[28:31]
	v_mfma_f32_16x16x32_bf16 v[24:27], v[170:173], v[210:213], v[24:27]
	v_mfma_f32_16x16x32_bf16 v[12:15], v[162:165], v[218:221], v[12:15]
	v_mfma_f32_16x16x32_bf16 v[8:11], v[170:173], v[218:221], v[8:11]
	s_setprio 0
	s_setprio 1
	v_mfma_f32_16x16x32_bf16 v[52:55], v[174:177], v[190:193], 0
	v_mfma_f32_16x16x32_bf16 v[48:51], v[182:185], v[190:193], 0
	v_mfma_f32_16x16x32_bf16 v[36:39], v[174:177], v[198:201], 0
	v_mfma_f32_16x16x32_bf16 v[32:35], v[182:185], v[198:201], 0
	v_mfma_f32_16x16x32_bf16 v[20:23], v[174:177], v[206:209], 0
	v_mfma_f32_16x16x32_bf16 v[16:19], v[182:185], v[206:209], 0
	v_mfma_f32_16x16x32_bf16 v[4:7], v[174:177], v[214:217], 0
	v_mfma_f32_16x16x32_bf16 v[0:3], v[182:185], v[214:217], 0
	v_mfma_f32_16x16x32_bf16 v[52:55], v[178:181], v[194:197], v[52:55]
	v_mfma_f32_16x16x32_bf16 v[48:51], v[186:189], v[194:197], v[48:51]
	v_mfma_f32_16x16x32_bf16 v[36:39], v[178:181], v[202:205], v[36:39]
	v_mfma_f32_16x16x32_bf16 v[32:35], v[186:189], v[202:205], v[32:35]
	v_mfma_f32_16x16x32_bf16 v[20:23], v[178:181], v[210:213], v[20:23]
	v_mfma_f32_16x16x32_bf16 v[16:19], v[186:189], v[210:213], v[16:19]
	v_mfma_f32_16x16x32_bf16 v[4:7], v[178:181], v[218:221], v[4:7]
	v_mfma_f32_16x16x32_bf16 v[0:3], v[186:189], v[218:221], v[0:3]
	s_setprio 0
	s_cbranch_vccz .Llw_p1_b
	s_waitcnt vmcnt(16)
.Llw_p1_b:
	s_barrier
	s_add_i32 s50, 0, 0x18000
	v_add_u32_e32 v161, s50, v147
	s_add_i32 s54, 0, 0x1c000
	ds_read_b128 v[140:143], v161
	ds_read_b128 v[162:165], v161 offset:1024
	ds_read_b128 v[166:169], v161 offset:2048
	ds_read_b128 v[170:173], v161 offset:3072
	v_add_u32_e32 v161, s54, v147
	ds_read_b128 v[174:177], v161
	ds_read_b128 v[178:181], v161 offset:1024
	ds_read_b128 v[182:185], v161 offset:2048
	ds_read_b128 v[186:189], v161 offset:3072
	s_add_u32 s52, s78, s34
	s_addc_u32 s53, s79, s35
	s_mov_b32 m0, s99
	v_lshl_add_u64 v[230:231], s[52:53], 0, v[130:131]
	ds_read_b128 v[190:193], v149 offset:32768
	ds_read_b128 v[194:197], v149 offset:33792
	ds_read_b128 v[198:201], v149 offset:34816
	ds_read_b128 v[202:205], v149 offset:35840
	ds_read_b128 v[206:209], v149 offset:36864
	ds_read_b128 v[210:213], v149 offset:37888
	ds_read_b128 v[214:217], v149 offset:38912
	ds_read_b128 v[218:221], v149 offset:39936
	global_load_lds_dwordx4 v[230:231], off
	v_lshl_add_u64 v[230:231], s[52:53], 0, v[132:133]
	s_mov_b32 m0, s76
	s_nop 0
	global_load_lds_dwordx4 v[230:231], off
	s_cbranch_vccnz .Llw_p2_a
	s_waitcnt vmcnt(16)
.Llw_p2_a:
	s_waitcnt lgkmcnt(0)
	s_barrier
	s_setprio 1
	s_waitcnt lgkmcnt(0)
	v_mfma_f32_16x16x32_bf16 v[126:129], v[140:143], v[190:193], v[126:129]
	v_mfma_f32_16x16x32_bf16 v[122:125], v[166:169], v[190:193], v[122:125]
	v_mfma_f32_16x16x32_bf16 v[110:113], v[140:143], v[198:201], v[110:113]
	v_mfma_f32_16x16x32_bf16 v[106:109], v[166:169], v[198:201], v[106:109]
	v_mfma_f32_16x16x32_bf16 v[92:95], v[140:143], v[206:209], v[92:95]
	v_mfma_f32_16x16x32_bf16 v[88:91], v[166:169], v[206:209], v[88:91]
	v_mfma_f32_16x16x32_bf16 v[76:79], v[140:143], v[214:217], v[76:79]
	v_mfma_f32_16x16x32_bf16 v[72:75], v[166:169], v[214:217], v[72:75]
	v_mfma_f32_16x16x32_bf16 v[126:129], v[162:165], v[194:197], v[126:129]
	v_mfma_f32_16x16x32_bf16 v[122:125], v[170:173], v[194:197], v[122:125]
	v_mfma_f32_16x16x32_bf16 v[110:113], v[162:165], v[202:205], v[110:113]
	v_mfma_f32_16x16x32_bf16 v[106:109], v[170:173], v[202:205], v[106:109]
	v_mfma_f32_16x16x32_bf16 v[92:95], v[162:165], v[210:213], v[92:95]
	v_mfma_f32_16x16x32_bf16 v[88:91], v[170:173], v[210:213], v[88:91]
	v_mfma_f32_16x16x32_bf16 v[76:79], v[162:165], v[218:221], v[76:79]
	v_mfma_f32_16x16x32_bf16 v[72:75], v[170:173], v[218:221], v[72:75]
	s_setprio 0
	s_setprio 1
	v_mfma_f32_16x16x32_bf16 v[118:121], v[174:177], v[190:193], v[118:121]
	v_mfma_f32_16x16x32_bf16 v[114:117], v[182:185], v[190:193], v[114:117]
	v_mfma_f32_16x16x32_bf16 v[102:105], v[174:177], v[198:201], v[102:105]
	v_mfma_f32_16x16x32_bf16 v[98:101], v[182:185], v[198:201], v[98:101]
	v_mfma_f32_16x16x32_bf16 v[84:87], v[174:177], v[206:209], v[84:87]
	v_mfma_f32_16x16x32_bf16 v[80:83], v[182:185], v[206:209], v[80:83]
	v_mfma_f32_16x16x32_bf16 v[68:71], v[174:177], v[214:217], v[68:71]
	v_mfma_f32_16x16x32_bf16 v[64:67], v[182:185], v[214:217], v[64:67]
	v_mfma_f32_16x16x32_bf16 v[118:121], v[178:181], v[194:197], v[118:121]
	v_mfma_f32_16x16x32_bf16 v[114:117], v[186:189], v[194:197], v[114:117]
	v_mfma_f32_16x16x32_bf16 v[102:105], v[178:181], v[202:205], v[102:105]
	v_mfma_f32_16x16x32_bf16 v[98:101], v[186:189], v[202:205], v[98:101]
	v_mfma_f32_16x16x32_bf16 v[84:87], v[178:181], v[210:213], v[84:87]
	v_mfma_f32_16x16x32_bf16 v[80:83], v[186:189], v[210:213], v[80:83]
	v_mfma_f32_16x16x32_bf16 v[68:71], v[178:181], v[218:221], v[68:71]
	v_mfma_f32_16x16x32_bf16 v[64:67], v[186:189], v[218:221], v[64:67]
	s_setprio 0
	s_cbranch_vccz .Llw_p2_b
	s_waitcnt vmcnt(16)

.Llw_p3_b:
	s_barrier
	s_add_u32 s42, s42, 0x100
	s_addc_u32 s43, s43, 0
	s_add_u32 s48, s48, 0x100
	s_addc_u32 s49, s49, 0
	s_cmp_ge_u32 s51, s64
	s_mov_b32 s50, s51
	s_cbranch_scc0 .LBB0_333
	s_branch .Lk_done
